# next-tile decode: group-size division (float-reciprocal sequence per tile) replaced by shift/mask since M=32768 always gives full groups of 8
# speedup vs baseline: 1.0087x; 1.0087x over previous
;     __host__ __device__ bool next(int i, Unit& u) const {
;         const long L = (long)i * G + c; if (L >= nwg) return false;
;         int wgid = (int)L; { const int q = nwg / NXCD, r = nwg % NXCD, xcd = wgid % NXCD, off = wgid / NXCD; wgid = (xcd < r ? xcd * (q + 1) : r * (q + 1) + (xcd - r) * q) + off; }
;         const int nig = WGM * nN, gid = wgid / nig, fm = gid * WGM, gsz = (nM - fm) < WGM ? (nM - fm) : WGM;
;         u.pm = fm + ((wgid % nig) % gsz); u.pn = (wgid % nig) / gsz; return true;
;     }
.LBB0_161:
	s_add_i32 s33, s33, 1
	v_readlane_b32 s4, v255, 0
	s_mul_i32 s3, s33, s23
	v_readlane_b32 s5, v255, 1
	s_mov_b32 s6, s4
	s_mul_hi_u32 s4, s33, s4
	s_add_i32 s3, s4, s3
	s_mul_i32 s4, s33, s6
	v_readlane_b32 s5, v255, 4
	s_add_u32 s4, s4, s5
	s_addc_u32 s5, s3, s22
	v_cmp_ge_i64_e32 vcc, s[4:5], v[222:223]
	v_cmp_lt_i64_e64 s[6:7], s[4:5], v[222:223]
	s_cbranch_vccnz .LBB0_163
	s_ashr_i32 s3, s4, 31
	s_lshr_b32 s3, s3, 29
	s_add_i32 s3, s4, s3
	s_ashr_i32 s5, s3, 3
	s_and_b32 s3, s3, -8
	s_sub_i32 s3, s4, s3
	s_lshr_b32 s4, s3, 31
	v_readlane_b32 s12, v255, 36
	s_or_b32 s4, s12, s4
	s_mul_i32 s3, s4, s3
	s_add_i32 s3, s3, s5
	s_abs_i32 s5, s3
	v_readlane_b32 s12, v255, 44
	s_mul_hi_u32 s12, s5, s12
	s_mul_i32 s13, s12, s88
	s_sub_i32 s5, s5, s13
	s_ashr_i32 s4, s3, 31
	s_add_i32 s13, s12, 1
	s_sub_i32 s14, s5, s88
	s_cmp_ge_u32 s5, s88
	s_cselect_b32 s12, s13, s12
	s_cselect_b32 s5, s14, s5
	s_add_i32 s13, s12, 1
	s_cmp_ge_u32 s5, s88
	s_cselect_b32 s5, s13, s12
	s_xor_b32 s5, s5, s4
	s_sub_i32 s4, s5, s4
	s_lshl_b32 s5, s4, 3
	s_mul_i32 s4, s4, s88
	s_sub_i32 s3, s3, s4
	s_lshr_b32 s37, s3, 3
	s_and_b32 s3, s3, 7
	s_add_i32 s44, s3, s5
